# v38
# baseline (speedup 1.0000x reference)
; DI unsigned pack2(float a, float b) { fl2_t v = {a, b}; bf2_t r = __builtin_convertvector(v, bf2_t); return __builtin_bit_cast(unsigned, r); }
; DI float sigmoidf_(float x) { return __builtin_amdgcn_rcpf(1.f + __builtin_amdgcn_exp2f(-1.4426950408889634f * x)); }
; DI float rl(float v, int srclane) { return __int_as_float(__builtin_amdgcn_readlane(__float_as_int(v), srclane)); }
; DI void epi_rows(const Params& p, int L, int ekind, const float* T, int rbase, int bcol) {
;     ...
;       for (int i = 0; i < 16; ++i) {
;         const float mu = rl(mu_l, i), rstd = rl(rstd_l, i);
;         const float* tr = T + (lr0 + i) * TSTR + c;
;         float g0 = rstd * (tr[0] - mu * csg0) + bwg0, g1 = rstd * (tr[1] - mu * csg1) + bwg1;
;         float u0 = rstd * (tr[128] - mu * csu0) + bwu0, u1 = rstd * (tr[129] - mu * csu1) + bwu1;
;         float a0 = g0 * sigmoidf_(g0) * u0, a1 = g1 * sigmoidf_(g1) * u1;
;         stg<unsigned>(ap + (size_t)i * DFF, pack2(a0, a1));
;       }
; DI void epi_dispatch(const Params& p, int L, int ekind, f32x4 (&acc)[2][2][4][2], int brow, int bcol, int, int, int, int) {
;     ...
;   for (int ai = 0; ai < 2; ++ai) {
;     __syncthreads();
;     #pragma unroll
;     for (int bj = 0; bj < 2; ++bj)
;       #pragma unroll
;       for (int m = 0; m < 4; ++m)
;         #pragma unroll
;         for (int n = 0; n < 2; ++n)
;           #pragma unroll
;           for (int j = 0; j < 4; ++j) tw[(m * 16 + j) * TSTR + bj * 128 + n * 16] = acc[ai][bj][m][n][j];
;     __syncthreads();
.LBB0_347:
	ds_read2st64_b64 v[98:101], v87 offset1:1
	ds_read2_b64 v[102:105], v87 offset0:130 offset1:194
	v_add_u32_e32 v118, 32, v87
	ds_read2st64_b64 v[106:109], v118 offset0:4 offset1:5
	v_add_u32_e32 v118, 48, v87
	ds_read2st64_b64 v[110:113], v118 offset0:6 offset1:7
	v_readlane_b32 s12, v68, s5
	v_readlane_b32 s24, v69, s5
	s_add_i32 s9, s5, 1
	s_waitcnt lgkmcnt(3)
	v_pk_fma_f32 v[88:89], v[70:71], s[12:13], v[98:99] op_sel_hi:[1,0,1] neg_lo:[1,0,0] neg_hi:[1,0,0]
	s_nop 0
	v_pk_fma_f32 v[88:89], s[24:25], v[88:89], v[74:75] op_sel_hi:[0,1,1]
	v_mul_f32_e32 v0, 0xbfb8aa3b, v88
	v_exp_f32_e32 v0, v0
	v_pk_fma_f32 v[92:93], v[72:73], s[12:13], v[100:101] op_sel_hi:[1,0,1] neg_lo:[1,0,0] neg_hi:[1,0,0]
	v_readlane_b32 s12, v68, s9
	v_pk_fma_f32 v[92:93], s[24:25], v[92:93], v[76:77] op_sel_hi:[0,1,1]
	v_add_f32_e32 v0, 1.0, v0
	v_rcp_f32_e32 v98, v0
	v_mul_f32_e32 v0, 0xbfb8aa3b, v89
	v_exp_f32_e32 v0, v0
	v_readlane_b32 s24, v69, s9
	s_add_i32 s9, s5, 2
	v_add_f32_e32 v0, 1.0, v0
	v_rcp_f32_e32 v99, v0
	s_nop 0
	v_pk_mul_f32 v[88:89], v[88:89], v[98:99]
	s_waitcnt lgkmcnt(2)
	v_mov_b64_e32 v[98:99], v[102:103]
	v_mov_b64_e32 v[100:101], v[104:105]
	v_pk_mul_f32 v[88:89], v[92:93], v[88:89]
	s_waitcnt lgkmcnt(2)
	v_pk_fma_f32 v[92:93], v[72:73], s[12:13], v[100:101] op_sel_hi:[1,0,1] neg_lo:[1,0,0] neg_hi:[1,0,0]
	v_cvt_pk_bf16_f32 v0, v88, v89
	v_add_co_u32_e32 v88, vcc, s22, v66
	v_pk_fma_f32 v[92:93], s[24:25], v[92:93], v[76:77] op_sel_hi:[0,1,1]
	s_nop 0
	v_addc_co_u32_e32 v89, vcc, -1, v67, vcc
	global_store_dword v[88:89], v0, off offset:-512
	v_pk_fma_f32 v[88:89], v[70:71], s[12:13], v[98:99] op_sel_hi:[1,0,1] neg_lo:[1,0,0] neg_hi:[1,0,0]
	v_readlane_b32 s12, v68, s9
	v_pk_fma_f32 v[88:89], s[24:25], v[88:89], v[74:75] op_sel_hi:[0,1,1]
	v_mul_f32_e32 v0, 0xbfb8aa3b, v88
	v_exp_f32_e32 v0, v0
	v_readlane_b32 s24, v69, s9
	s_add_i32 s9, s5, 3
	s_add_i32 s5, s5, 4
	v_add_f32_e32 v0, 1.0, v0
	v_rcp_f32_e32 v98, v0
	v_mul_f32_e32 v0, 0xbfb8aa3b, v89
	v_exp_f32_e32 v0, v0
	s_cmp_lg_u32 s5, 16
	v_add_f32_e32 v0, 1.0, v0
	v_rcp_f32_e32 v99, v0
	s_nop 0
	v_pk_mul_f32 v[88:89], v[88:89], v[98:99]
	s_nop 0
	v_pk_mul_f32 v[88:89], v[92:93], v[88:89]
	s_nop 0
	v_cvt_pk_bf16_f32 v0, v88, v89
	v_add_co_u32_e32 v88, vcc, s83, v66
	s_nop 1
	v_addc_co_u32_e32 v89, vcc, -1, v67, vcc
	global_store_dword v[88:89], v0, off offset:-3072
	v_add_u32_e32 v0, 32, v87
	s_waitcnt lgkmcnt(1)
	v_mov_b64_e32 v[98:99], v[106:107]
	v_mov_b64_e32 v[100:101], v[108:109]
	s_waitcnt lgkmcnt(1)
	v_pk_fma_f32 v[88:89], v[70:71], s[12:13], v[98:99] op_sel_hi:[1,0,1] neg_lo:[1,0,0] neg_hi:[1,0,0]
	s_nop 0
	v_pk_fma_f32 v[88:89], s[24:25], v[88:89], v[74:75] op_sel_hi:[0,1,1]
	v_mul_f32_e32 v0, 0xbfb8aa3b, v88
	v_exp_f32_e32 v0, v0
	v_pk_fma_f32 v[92:93], v[72:73], s[12:13], v[100:101] op_sel_hi:[1,0,1] neg_lo:[1,0,0] neg_hi:[1,0,0]
	v_readlane_b32 s12, v68, s9
	v_pk_fma_f32 v[92:93], s[24:25], v[92:93], v[76:77] op_sel_hi:[0,1,1]
	v_add_f32_e32 v0, 1.0, v0
	v_rcp_f32_e32 v98, v0
	v_mul_f32_e32 v0, 0xbfb8aa3b, v89
	v_exp_f32_e32 v0, v0
	v_readlane_b32 s24, v69, s9
	v_add_f32_e32 v0, 1.0, v0
	v_rcp_f32_e32 v99, v0
	s_nop 0
	v_pk_mul_f32 v[88:89], v[88:89], v[98:99]
	s_nop 0
	v_pk_mul_f32 v[88:89], v[92:93], v[88:89]
	s_nop 0
	v_cvt_pk_bf16_f32 v0, v88, v89
	v_add_co_u32_e32 v88, vcc, s84, v66
	s_nop 1
	v_addc_co_u32_e32 v89, vcc, -1, v67, vcc
	global_store_dword v[88:89], v0, off offset:-1536
	v_add_u32_e32 v0, 48, v87
	s_waitcnt lgkmcnt(0)
	v_mov_b64_e32 v[98:99], v[110:111]
	v_mov_b64_e32 v[100:101], v[112:113]
	v_add_u32_e32 v87, 0x1040, v87
	s_waitcnt lgkmcnt(0)
	v_pk_fma_f32 v[88:89], v[70:71], s[12:13], v[98:99] op_sel_hi:[1,0,1] neg_lo:[1,0,0] neg_hi:[1,0,0]
	s_nop 0
	v_pk_fma_f32 v[88:89], s[24:25], v[88:89], v[74:75] op_sel_hi:[0,1,1]
	v_mul_f32_e32 v0, 0xbfb8aa3b, v88
	v_exp_f32_e32 v0, v0
	v_pk_fma_f32 v[92:93], v[72:73], s[12:13], v[100:101] op_sel_hi:[1,0,1] neg_lo:[1,0,0] neg_hi:[1,0,0]
	v_add_f32_e32 v0, 1.0, v0
	v_rcp_f32_e32 v98, v0
	v_mul_f32_e32 v0, 0xbfb8aa3b, v89
	v_exp_f32_e32 v0, v0
	v_pk_fma_f32 v[92:93], s[24:25], v[92:93], v[76:77] op_sel_hi:[0,1,1]
	v_add_f32_e32 v0, 1.0, v0
	v_rcp_f32_e32 v99, v0
	s_nop 0
	v_pk_mul_f32 v[88:89], v[88:89], v[98:99]
	s_nop 0
	v_pk_mul_f32 v[88:89], v[92:93], v[88:89]
	s_nop 0
	v_cvt_pk_bf16_f32 v0, v88, v89
	global_store_dword v[66:67], v0, off
	v_lshl_add_u64 v[66:67], v[66:67], 0, s[88:89]
	s_cbranch_scc1 .LBB0_347
	s_barrier
	ds_write2_b32 v130, v2, v18 offset1:16
	ds_write2_b32 v114, v3, v19 offset0:4 offset1:20
	ds_write2_b32 v115, v4, v20 offset0:8 offset1:24
	ds_write2_b32 v116, v5, v21 offset0:12 offset1:28
	ds_write2_b32 v117, v6, v22 offset0:64 offset1:80
	ds_write2_b32 v82, v7, v23 offset0:68 offset1:84
	ds_write2_b32 v83, v8, v24 offset0:72 offset1:88
	ds_write2_b32 v84, v9, v25 offset0:76 offset1:92
	ds_write2_b32 v96, v10, v26 offset0:128 offset1:144
	ds_write2_b32 v85, v11, v27 offset0:132 offset1:148
	ds_write2_b32 v79, v12, v28 offset0:136 offset1:152
	ds_write2_b32 v80, v13, v29 offset0:140 offset1:156
	ds_write2_b32 v97, v14, v30 offset0:192 offset1:208
	ds_write2_b32 v81, v15, v31 offset0:196 offset1:212
	ds_write2_b32 v94, v16, v32 offset0:200 offset1:216
	ds_write2_b32 v95, v17, v33 offset0:204 offset1:220
	ds_write2_b32 v130, v34, v50 offset0:128 offset1:144
	ds_write2_b32 v114, v35, v51 offset0:132 offset1:148
	ds_write2_b32 v115, v36, v52 offset0:136 offset1:152
	ds_write2_b32 v116, v37, v53 offset0:140 offset1:156
	ds_write2_b32 v117, v38, v54 offset0:192 offset1:208
	ds_write2_b32 v82, v39, v55 offset0:196 offset1:212
	ds_write2_b32 v83, v40, v56 offset0:200 offset1:216
	ds_write2_b32 v84, v41, v57 offset0:204 offset1:220
	ds_write2_b32 v85, v42, v58 offset1:16
	ds_write2_b32 v79, v43, v59 offset0:4 offset1:20
	ds_write2_b32 v80, v44, v60 offset0:8 offset1:24
	ds_write2_b32 v90, v45, v61 offset0:12 offset1:28
	ds_write2_b32 v81, v46, v62 offset0:64 offset1:80
	ds_write2_b32 v94, v47, v63 offset0:68 offset1:84
	ds_write2_b32 v95, v48, v64 offset0:72 offset1:88
	ds_write2_b32 v86, v49, v65 offset0:76 offset1:92
	s_mov_b64 s[12:13], s[70:71]
	v_mov_b32_e32 v15, v178
	s_waitcnt lgkmcnt(0)
	s_barrier
; DI float fxc(const i64* p) { return (float)(*p) * FXC_INV; }
; DI RowStat row_stat(const i64* st, int row) {
;   float s = (float)st[2 * (size_t)row] * FXS_INV, q = (float)st[2 * (size_t)row + 1] * FXS_INV;
;   float mu = s * (1.f / 1024.f);
;   float var = fmaxf(q * (1.f / 1024.f) - mu * mu, 0.f);
;   RowStat r; r.mu = mu; r.rstd = rsqrtf(var + 1e-5f); return r;
; }
; DI void epi_rows(const Params& p, int L, int ekind, const float* T, int rbase, int bcol) {
;     ...
;       float csg0 = 0, csg1 = 0, csu0 = 0, csu1 = 0, bwg0 = 0, bwg1 = 0, bwu0 = 0, bwu1 = 0;
;       float mu_l = 0.f, rstd_l = 1.f;
;       if (st) { const i64* q = cs + co + bcol + c; const i64* r = bw + co + bcol + c;
;         csg0 = fxc(q); csg1 = fxc(q + 1); csu0 = fxc(q + 128); csu1 = fxc(q + 129); bwg0 = fxc(r); bwg1 = fxc(r + 1); bwu0 = fxc(r + 128); bwu1 = fxc(r + 129);
;         RowStat rs = row_stat(st, myrow); mu_l = rs.mu; rstd_l = rs.rstd; }
	v_readlane_b32 s24, v254, 5
	v_readfirstlane_b32 s5, v15
	s_ashr_i32 s9, s5, 2
	v_lshlrev_b32_e32 v0, 1, v15
	v_readlane_b32 s25, v254, 6
	s_and_b32 s5, s9, -16
	s_andn2_b64 vcc, exec, s[24:25]
	v_and_b32_e32 v14, 0x7e, v0
	s_cbranch_vccnz .LBB0_350
	v_readlane_b32 s24, v255, 12
	v_readlane_b32 s25, v255, 13
	s_add_i32 s8, s5, s8
	s_lshl_b64 s[24:25], s[24:25], 3
	v_and_or_b32 v2, v15, 15, s8
	s_add_u32 s8, s12, s24
	s_addc_u32 s19, s13, s25
	s_lshl_b64 s[6:7], s[6:7], 3
	s_add_u32 s6, s8, s6
	s_addc_u32 s7, s19, s7
	v_lshlrev_b32_e32 v0, 3, v14
	v_lshl_add_u64 v[10:11], s[6:7], 0, v[0:1]
	s_mov_b64 s[6:7], 0x38e000
	v_lshl_add_u64 v[12:13], v[10:11], 0, s[6:7]
	s_mov_b64 s[6:7], 0x3c9000
	v_lshl_add_u64 v[4:5], v[10:11], 0, s[6:7]
	s_mov_b32 s6, 0x38e000
	v_add_co_u32_e32 v6, vcc, s6, v10
	flat_load_dwordx4 v[16:19], v[12:13] offset:1024
	s_nop 0
	v_addc_co_u32_e32 v7, vcc, 0, v11, vcc
	flat_load_dwordx4 v[6:9], v[6:7]
	s_mov_b32 s8, 0x2f800000
	s_mov_b32 s6, 0x3c9000
	v_add_co_u32_e32 v10, vcc, s6, v10
	s_mov_b32 s6, 0x104000
	s_nop 0
	v_addc_co_u32_e32 v11, vcc, 0, v11, vcc
	s_waitcnt vmcnt(0) lgkmcnt(0)
	v_xor_b32_e32 v0, v8, v9
	v_ashrrev_i32_e32 v0, 31, v0
	v_ffbh_i32_e32 v3, v9
	v_add_u32_e32 v0, 32, v0
	v_add_u32_e32 v3, -1, v3
	v_min_u32_e32 v0, v3, v0
	v_lshlrev_b64 v[8:9], v0, v[8:9]
	v_min_u32_e32 v3, 1, v8
	v_or_b32_e32 v3, v9, v3
	v_cvt_f32_i32_e32 v3, v3
	v_sub_u32_e32 v0, 32, v0
	v_ldexp_f32 v9, v3, v0
	v_xor_b32_e32 v0, v6, v7
	v_ashrrev_i32_e32 v0, 31, v0
	v_ffbh_i32_e32 v3, v7
	v_add_u32_e32 v0, 32, v0
	v_add_u32_e32 v3, -1, v3
	v_min_u32_e32 v0, v3, v0
	v_lshlrev_b64 v[6:7], v0, v[6:7]
	v_min_u32_e32 v3, 1, v6
	v_or_b32_e32 v3, v7, v3
	v_cvt_f32_i32_e32 v3, v3
	v_sub_u32_e32 v0, 32, v0
	v_ldexp_f32 v8, v3, v0
	v_xor_b32_e32 v0, v18, v19
	v_ashrrev_i32_e32 v0, 31, v0
	v_ffbh_i32_e32 v3, v19
	v_add_u32_e32 v0, 32, v0
	v_add_u32_e32 v3, -1, v3
	v_min_u32_e32 v0, v3, v0
	v_pk_mul_f32 v[6:7], v[8:9], s[8:9] op_sel_hi:[1,0]
	v_lshlrev_b64 v[8:9], v0, v[18:19]
	v_min_u32_e32 v3, 1, v8
	v_or_b32_e32 v3, v9, v3
	v_cvt_f32_i32_e32 v3, v3
	v_sub_u32_e32 v0, 32, v0
	v_ldexp_f32 v9, v3, v0
	v_xor_b32_e32 v0, v16, v17
	v_ashrrev_i32_e32 v0, 31, v0
	v_ffbh_i32_e32 v3, v17
	v_add_u32_e32 v0, 32, v0
	v_add_u32_e32 v3, -1, v3
	v_min_u32_e32 v0, v3, v0
	v_lshlrev_b64 v[12:13], v0, v[16:17]
	v_min_u32_e32 v3, 1, v12
	v_or_b32_e32 v3, v13, v3
	flat_load_dwordx4 v[10:13], v[10:11]
	v_cvt_f32_i32_e32 v3, v3
	flat_load_dwordx4 v[16:19], v[4:5] offset:1024
	v_sub_u32_e32 v0, 32, v0
	v_ldexp_f32 v8, v3, v0
	v_pk_mul_f32 v[8:9], v[8:9], s[8:9] op_sel_hi:[1,0]
	s_waitcnt vmcnt(0) lgkmcnt(0)
	v_xor_b32_e32 v0, v12, v13
	v_ashrrev_i32_e32 v0, 31, v0
	v_ffbh_i32_e32 v3, v13
	v_add_u32_e32 v0, 32, v0
	v_add_u32_e32 v3, -1, v3
	v_min_u32_e32 v0, v3, v0
	v_lshlrev_b64 v[12:13], v0, v[12:13]
	v_min_u32_e32 v3, 1, v12
	v_or_b32_e32 v3, v13, v3
	v_cvt_f32_i32_e32 v3, v3
	v_sub_u32_e32 v0, 32, v0
	v_ldexp_f32 v13, v3, v0
	v_xor_b32_e32 v0, v10, v11
	v_ashrrev_i32_e32 v0, 31, v0
	v_ffbh_i32_e32 v3, v11
	v_add_u32_e32 v0, 32, v0
	v_add_u32_e32 v3, -1, v3
	v_min_u32_e32 v0, v3, v0
	v_lshlrev_b64 v[10:11], v0, v[10:11]
	v_min_u32_e32 v3, 1, v10
	v_or_b32_e32 v3, v11, v3
	v_cvt_f32_i32_e32 v3, v3
	v_sub_u32_e32 v0, 32, v0
	v_ldexp_f32 v12, v3, v0
	v_xor_b32_e32 v0, v18, v19
	v_ashrrev_i32_e32 v0, 31, v0
	v_ffbh_i32_e32 v3, v19
	v_add_u32_e32 v0, 32, v0
	v_add_u32_e32 v3, -1, v3
	v_min_u32_e32 v0, v3, v0
	v_lshlrev_b64 v[4:5], v0, v[18:19]
	v_min_u32_e32 v3, 1, v4
	v_or_b32_e32 v3, v5, v3
	v_cvt_f32_i32_e32 v3, v3
	v_sub_u32_e32 v0, 32, v0
	v_pk_mul_f32 v[10:11], v[12:13], s[8:9] op_sel_hi:[1,0]
	v_ldexp_f32 v5, v3, v0
	v_xor_b32_e32 v0, v16, v17
	v_ashrrev_i32_e32 v0, 31, v0
	v_ffbh_i32_e32 v3, v17
	v_add_u32_e32 v0, 32, v0
	v_add_u32_e32 v3, -1, v3
	v_min_u32_e32 v0, v3, v0
	v_lshlrev_b64 v[12:13], v0, v[16:17]
	v_min_u32_e32 v3, 1, v12
	v_or_b32_e32 v3, v13, v3
	v_cvt_f32_i32_e32 v3, v3
	v_sub_u32_e32 v0, 32, v0
	v_ldexp_f32 v4, v3, v0
	v_ashrrev_i32_e32 v3, 31, v2
	v_lshl_add_u64 v[2:3], v[2:3], 4, s[12:13]
	v_add_co_u32_e32 v2, vcc, s6, v2
	v_pk_mul_f32 v[12:13], v[4:5], s[8:9] op_sel_hi:[1,0]
	s_nop 0
	v_addc_co_u32_e32 v3, vcc, 0, v3, vcc
	flat_load_dwordx4 v[2:5], v[2:3]
	s_mov_b32 s6, 0x3a800000
	s_waitcnt vmcnt(0) lgkmcnt(0)
	v_xor_b32_e32 v0, v2, v3
	v_ashrrev_i32_e32 v0, 31, v0
	v_ffbh_i32_e32 v16, v3
	v_add_u32_e32 v0, 32, v0
	v_add_u32_e32 v16, -1, v16
	v_min_u32_e32 v0, v16, v0
	v_lshlrev_b64 v[2:3], v0, v[2:3]
	v_min_u32_e32 v2, 1, v2
	v_or_b32_e32 v2, v3, v2
	v_cvt_f32_i32_e32 v2, v2
	v_sub_u32_e32 v0, 32, v0
	v_ffbh_i32_e32 v3, v5
	v_add_u32_e32 v3, -1, v3
	v_ldexp_f32 v0, v2, v0
	v_xor_b32_e32 v2, v4, v5
	v_ashrrev_i32_e32 v2, 31, v2
	v_add_u32_e32 v2, 32, v2
	v_min_u32_e32 v16, v3, v2
	v_lshlrev_b64 v[2:3], v16, v[4:5]
	v_min_u32_e32 v2, 1, v2
	v_or_b32_e32 v2, v3, v2
	v_cvt_f32_i32_e32 v2, v2
	v_mul_f32_e32 v0, 0x33800000, v0
	v_sub_u32_e32 v3, 32, v16
	v_mul_f32_e32 v4, 0x3a800000, v0
	v_ldexp_f32 v2, v2, v3
	v_mul_f32_e32 v2, 0x33800000, v2
	v_mul_f32_e32 v0, v4, v4
	v_fma_f32 v0, v2, s6, -v0
	v_max_f32_e32 v0, 0, v0
	v_add_f32_e32 v0, 0x3727c5ac, v0
	s_mov_b32 s6, 0x800000
	v_cmp_gt_f32_e32 vcc, s6, v0
	v_mul_f32_e32 v2, 0x4b800000, v0
	s_nop 0
	v_cndmask_b32_e32 v0, v0, v2, vcc
	v_rsq_f32_e32 v0, v0
	s_nop 0
	v_mul_f32_e32 v2, 0x45800000, v0
	v_cndmask_b32_e32 v5, v0, v2, vcc
	s_cbranch_execz .LBB0_351
	s_branch .LBB0_352

; DI unsigned pack2(float a, float b) { fl2_t v = {a, b}; bf2_t r = __builtin_convertvector(v, bf2_t); return __builtin_bit_cast(unsigned, r); }
; DI float sigmoidf_(float x) { return __builtin_amdgcn_rcpf(1.f + __builtin_amdgcn_exp2f(-1.4426950408889634f * x)); }
; DI float rl(float v, int srclane) { return __int_as_float(__builtin_amdgcn_readlane(__float_as_int(v), srclane)); }
; DI void epi_rows(const Params& p, int L, int ekind, const float* T, int rbase, int bcol) {
;     ...
;       for (int i = 0; i < 16; ++i) {
;         const float mu = rl(mu_l, i), rstd = rl(rstd_l, i);
;         const float* tr = T + (lr0 + i) * TSTR + c;
;         float g0 = rstd * (tr[0] - mu * csg0) + bwg0, g1 = rstd * (tr[1] - mu * csg1) + bwg1;
;         float u0 = rstd * (tr[128] - mu * csu0) + bwu0, u1 = rstd * (tr[129] - mu * csu1) + bwu1;
;         float a0 = g0 * sigmoidf_(g0) * u0, a1 = g1 * sigmoidf_(g1) * u1;
;         stg<unsigned>(ap + (size_t)i * DFF, pack2(a0, a1));
;       }
.LBB0_353:
	ds_read2st64_b64 v[16:19], v15 offset1:1
	ds_read2_b64 v[102:105], v15 offset0:130 offset1:194
	v_add_u32_e32 v118, 32, v15
	ds_read2st64_b64 v[106:109], v118 offset0:4 offset1:5
	v_add_u32_e32 v118, 48, v15
	ds_read2st64_b64 v[110:113], v118 offset0:6 offset1:7
	v_readlane_b32 s6, v4, s4
	v_readlane_b32 s8, v5, s4
	s_add_i32 s5, s4, 1
	s_waitcnt lgkmcnt(3)
	v_pk_fma_f32 v[16:17], v[6:7], s[6:7], v[16:17] op_sel_hi:[1,0,1] neg_lo:[1,0,0] neg_hi:[1,0,0]
	s_nop 0
	v_pk_fma_f32 v[16:17], s[8:9], v[16:17], v[10:11] op_sel_hi:[0,1,1]
	v_mul_f32_e32 v0, 0xbfb8aa3b, v16
	v_exp_f32_e32 v0, v0
	v_pk_fma_f32 v[18:19], v[8:9], s[6:7], v[18:19] op_sel_hi:[1,0,1] neg_lo:[1,0,0] neg_hi:[1,0,0]
	v_readlane_b32 s6, v4, s5
	v_pk_fma_f32 v[18:19], s[8:9], v[18:19], v[12:13] op_sel_hi:[0,1,1]
	v_add_f32_e32 v0, 1.0, v0
	v_rcp_f32_e32 v20, v0
	v_mul_f32_e32 v0, 0xbfb8aa3b, v17
	v_exp_f32_e32 v0, v0
	v_readlane_b32 s8, v5, s5
	s_add_i32 s5, s4, 2
	v_add_f32_e32 v0, 1.0, v0
	v_rcp_f32_e32 v21, v0
	s_nop 0
	v_pk_mul_f32 v[16:17], v[16:17], v[20:21]
	s_nop 0
	v_pk_mul_f32 v[16:17], v[18:19], v[16:17]
	s_nop 0
	v_cvt_pk_bf16_f32 v0, v16, v17
	v_add_co_u32_e32 v16, vcc, s22, v2
	s_nop 1
	v_addc_co_u32_e32 v17, vcc, -1, v3, vcc
	global_store_dword v[16:17], v0, off offset:-512
	s_waitcnt lgkmcnt(2)
	v_mov_b64_e32 v[16:17], v[102:103]
	v_mov_b64_e32 v[18:19], v[104:105]
	s_waitcnt lgkmcnt(2)
	v_pk_fma_f32 v[16:17], v[6:7], s[6:7], v[16:17] op_sel_hi:[1,0,1] neg_lo:[1,0,0] neg_hi:[1,0,0]
	s_nop 0
	v_pk_fma_f32 v[16:17], s[8:9], v[16:17], v[10:11] op_sel_hi:[0,1,1]
	v_mul_f32_e32 v0, 0xbfb8aa3b, v16
	v_exp_f32_e32 v0, v0
	v_pk_fma_f32 v[18:19], v[8:9], s[6:7], v[18:19] op_sel_hi:[1,0,1] neg_lo:[1,0,0] neg_hi:[1,0,0]
	v_readlane_b32 s6, v4, s5
	v_pk_fma_f32 v[18:19], s[8:9], v[18:19], v[12:13] op_sel_hi:[0,1,1]
	v_add_f32_e32 v0, 1.0, v0
	v_rcp_f32_e32 v20, v0
	v_mul_f32_e32 v0, 0xbfb8aa3b, v17
	v_exp_f32_e32 v0, v0
	v_readlane_b32 s8, v5, s5
	s_add_i32 s5, s4, 3
	s_add_i32 s4, s4, 4
	v_add_f32_e32 v0, 1.0, v0
	v_rcp_f32_e32 v21, v0
	s_cmp_lg_u32 s4, 16
	v_pk_mul_f32 v[16:17], v[16:17], v[20:21]
	s_nop 0
	v_pk_mul_f32 v[16:17], v[18:19], v[16:17]
	s_nop 0
	v_cvt_pk_bf16_f32 v0, v16, v17
	v_add_co_u32_e32 v16, vcc, s83, v2
	s_nop 1
	v_addc_co_u32_e32 v17, vcc, -1, v3, vcc
	global_store_dword v[16:17], v0, off offset:-3072
	v_add_u32_e32 v0, 32, v15
	s_waitcnt lgkmcnt(1)
	v_mov_b64_e32 v[16:17], v[106:107]
	v_mov_b64_e32 v[18:19], v[108:109]
	s_waitcnt lgkmcnt(1)
	v_pk_fma_f32 v[16:17], v[6:7], s[6:7], v[16:17] op_sel_hi:[1,0,1] neg_lo:[1,0,0] neg_hi:[1,0,0]
	s_nop 0
	v_pk_fma_f32 v[16:17], s[8:9], v[16:17], v[10:11] op_sel_hi:[0,1,1]
	v_mul_f32_e32 v0, 0xbfb8aa3b, v16
	v_exp_f32_e32 v0, v0
	v_pk_fma_f32 v[18:19], v[8:9], s[6:7], v[18:19] op_sel_hi:[1,0,1] neg_lo:[1,0,0] neg_hi:[1,0,0]
	v_readlane_b32 s6, v4, s5
	v_pk_fma_f32 v[18:19], s[8:9], v[18:19], v[12:13] op_sel_hi:[0,1,1]
	v_add_f32_e32 v0, 1.0, v0
	v_rcp_f32_e32 v20, v0
	v_mul_f32_e32 v0, 0xbfb8aa3b, v17
	v_exp_f32_e32 v0, v0
	v_readlane_b32 s8, v5, s5
	v_add_f32_e32 v0, 1.0, v0
	v_rcp_f32_e32 v21, v0
	s_nop 0
	v_pk_mul_f32 v[16:17], v[16:17], v[20:21]
	s_nop 0
	v_pk_mul_f32 v[16:17], v[18:19], v[16:17]
	s_nop 0
	v_cvt_pk_bf16_f32 v0, v16, v17
	v_add_co_u32_e32 v16, vcc, s84, v2
	s_nop 1
	v_addc_co_u32_e32 v17, vcc, -1, v3, vcc
	global_store_dword v[16:17], v0, off offset:-1536
	v_add_u32_e32 v0, 48, v15
	s_waitcnt lgkmcnt(0)
	v_mov_b64_e32 v[16:17], v[110:111]
	v_mov_b64_e32 v[18:19], v[112:113]
	v_add_u32_e32 v15, 0x1040, v15
	s_waitcnt lgkmcnt(0)
	v_pk_fma_f32 v[16:17], v[6:7], s[6:7], v[16:17] op_sel_hi:[1,0,1] neg_lo:[1,0,0] neg_hi:[1,0,0]
	s_nop 0
	v_pk_fma_f32 v[16:17], s[8:9], v[16:17], v[10:11] op_sel_hi:[0,1,1]
	v_mul_f32_e32 v0, 0xbfb8aa3b, v16
	v_exp_f32_e32 v0, v0
	v_pk_fma_f32 v[18:19], v[8:9], s[6:7], v[18:19] op_sel_hi:[1,0,1] neg_lo:[1,0,0] neg_hi:[1,0,0]
	v_add_f32_e32 v0, 1.0, v0
	v_rcp_f32_e32 v20, v0
	v_mul_f32_e32 v0, 0xbfb8aa3b, v17
	v_exp_f32_e32 v0, v0
	v_pk_fma_f32 v[18:19], s[8:9], v[18:19], v[12:13] op_sel_hi:[0,1,1]
	v_add_f32_e32 v0, 1.0, v0
	v_rcp_f32_e32 v21, v0
	s_nop 0
	v_pk_mul_f32 v[16:17], v[16:17], v[20:21]
	s_nop 0
	v_pk_mul_f32 v[16:17], v[18:19], v[16:17]
	s_nop 0
	v_cvt_pk_bf16_f32 v0, v16, v17
	global_store_dword v[2:3], v0, off
	v_lshl_add_u64 v[2:3], v[2:3], 0, s[88:89]
	s_cbranch_scc1 .LBB0_353
	s_barrier
	v_readlane_b32 s4, v254, 3
	s_add_i32 s18, s18, s4
	s_cmpk_lt_i32 s18, 0xb2c
	v_readlane_b32 s5, v254, 4
	s_cbranch_scc1 .LBB0_332

; DI unsigned pack2(float a, float b) { fl2_t v = {a, b}; bf2_t r = __builtin_convertvector(v, bf2_t); return __builtin_bit_cast(unsigned, r); }
; DI float sigmoidf_(float x) { return __builtin_amdgcn_rcpf(1.f + __builtin_amdgcn_exp2f(-1.4426950408889634f * x)); }
; DI float rl(float v, int srclane) { return __int_as_float(__builtin_amdgcn_readlane(__float_as_int(v), srclane)); }
; DI void epi_rows(const Params& p, int L, int ekind, const float* T, int rbase, int bcol) {
;     ...
;       for (int i = 0; i < 16; ++i) {
;         const float mu = rl(mu_l, i), rstd = rl(rstd_l, i);
;         const float* tr = T + (lr0 + i) * TSTR + c;
;         float g0 = rstd * (tr[0] - mu * csg0) + bwg0, g1 = rstd * (tr[1] - mu * csg1) + bwg1;
;         float u0 = rstd * (tr[128] - mu * csu0) + bwu0, u1 = rstd * (tr[129] - mu * csu1) + bwu1;
;         float a0 = g0 * sigmoidf_(g0) * u0, a1 = g1 * sigmoidf_(g1) * u1;
;         stg<unsigned>(ap + (size_t)i * DFF, pack2(a0, a1));
;       }
; DI void epi_dispatch(const Params& p, int L, int ekind, f32x4 (&acc)[2][2][4][2], int brow, int bcol, int, int, int, int) {
;     ...
;   for (int ai = 0; ai < 2; ++ai) {
;     __syncthreads();
;     #pragma unroll
;     for (int bj = 0; bj < 2; ++bj)
;       #pragma unroll
;       for (int m = 0; m < 4; ++m)
;         #pragma unroll
;         for (int n = 0; n < 2; ++n)
;           #pragma unroll
;           for (int j = 0; j < 4; ++j) tw[(m * 16 + j) * TSTR + bj * 128 + n * 16] = acc[ai][bj][m][n][j];
;     __syncthreads();
.LBB0_1897:
	ds_read2st64_b64 v[96:99], v89 offset1:1
	ds_read2_b64 v[102:105], v89 offset0:130 offset1:194
	v_add_u32_e32 v118, 32, v89
	ds_read2st64_b64 v[106:109], v118 offset0:4 offset1:5
	v_add_u32_e32 v118, 48, v89
	ds_read2st64_b64 v[110:113], v118 offset0:6 offset1:7
	v_readlane_b32 s14, v87, s5
	v_readlane_b32 s16, v88, s5
	s_waitcnt lgkmcnt(3)
	v_pk_fma_f32 v[92:93], v[66:67], s[14:15], v[96:97] op_sel_hi:[1,0,1] neg_lo:[1,0,0] neg_hi:[1,0,0]
	s_nop 0
	v_pk_fma_f32 v[92:93], s[16:17], v[92:93], v[70:71] op_sel_hi:[0,1,1]
	v_mul_f32_e32 v0, 0xbfb8aa3b, v92
	v_exp_f32_e32 v0, v0
	v_pk_fma_f32 v[96:97], v[68:69], s[14:15], v[98:99] op_sel_hi:[1,0,1] neg_lo:[1,0,0] neg_hi:[1,0,0]
	s_add_i32 s15, s5, 1
	v_pk_fma_f32 v[96:97], s[16:17], v[96:97], v[72:73] op_sel_hi:[0,1,1]
	v_add_f32_e32 v0, 1.0, v0
	v_rcp_f32_e32 v98, v0
	v_mul_f32_e32 v0, 0xbfb8aa3b, v93
	v_exp_f32_e32 v0, v0
	v_readlane_b32 s14, v87, s15
	v_readlane_b32 s16, v88, s15
	v_add_f32_e32 v0, 1.0, v0
	v_rcp_f32_e32 v99, v0
	s_nop 0
	v_pk_mul_f32 v[92:93], v[92:93], v[98:99]
	s_nop 0
	v_pk_mul_f32 v[92:93], v[96:97], v[92:93]
	s_waitcnt lgkmcnt(2)
	v_mov_b64_e32 v[96:97], v[102:103]
	v_mov_b64_e32 v[98:99], v[104:105]
	v_cvt_pk_bf16_f32 v0, v92, v93
	v_add_co_u32_e32 v92, vcc, s22, v74
	s_nop 1
	v_addc_co_u32_e32 v93, vcc, -1, v75, vcc
	global_store_dword v[92:93], v0, off offset:-512
	s_waitcnt lgkmcnt(2)
	v_pk_fma_f32 v[92:93], v[66:67], s[14:15], v[96:97] op_sel_hi:[1,0,1] neg_lo:[1,0,0] neg_hi:[1,0,0]
	v_pk_fma_f32 v[96:97], v[68:69], s[14:15], v[98:99] op_sel_hi:[1,0,1] neg_lo:[1,0,0] neg_hi:[1,0,0]
	v_pk_fma_f32 v[92:93], s[16:17], v[92:93], v[70:71] op_sel_hi:[0,1,1]
	v_mul_f32_e32 v0, 0xbfb8aa3b, v92
	v_exp_f32_e32 v0, v0
	v_pk_fma_f32 v[96:97], s[16:17], v[96:97], v[72:73] op_sel_hi:[0,1,1]
	s_add_i32 s15, s5, 2
	v_readlane_b32 s14, v87, s15
	v_add_f32_e32 v0, 1.0, v0
	v_rcp_f32_e32 v98, v0
	v_mul_f32_e32 v0, 0xbfb8aa3b, v93
	v_exp_f32_e32 v0, v0
	v_readlane_b32 s16, v88, s15
	v_add_f32_e32 v0, 1.0, v0
	v_rcp_f32_e32 v99, v0
	s_nop 0
	v_pk_mul_f32 v[92:93], v[92:93], v[98:99]
	s_nop 0
	v_pk_mul_f32 v[92:93], v[96:97], v[92:93]
	s_nop 0
	v_cvt_pk_bf16_f32 v0, v92, v93
	v_add_co_u32_e32 v92, vcc, s83, v74
	s_nop 1
	v_addc_co_u32_e32 v93, vcc, -1, v75, vcc
	global_store_dword v[92:93], v0, off offset:-3072
	v_add_u32_e32 v0, 32, v89
	s_waitcnt lgkmcnt(1)
	v_mov_b64_e32 v[96:97], v[106:107]
	v_mov_b64_e32 v[98:99], v[108:109]
	s_waitcnt lgkmcnt(1)
	v_pk_fma_f32 v[92:93], v[66:67], s[14:15], v[96:97] op_sel_hi:[1,0,1] neg_lo:[1,0,0] neg_hi:[1,0,0]
	s_nop 0
	v_pk_fma_f32 v[92:93], s[16:17], v[92:93], v[70:71] op_sel_hi:[0,1,1]
	v_mul_f32_e32 v0, 0xbfb8aa3b, v92
	v_exp_f32_e32 v0, v0
	v_pk_fma_f32 v[96:97], v[68:69], s[14:15], v[98:99] op_sel_hi:[1,0,1] neg_lo:[1,0,0] neg_hi:[1,0,0]
	s_add_i32 s15, s5, 3
	v_pk_fma_f32 v[96:97], s[16:17], v[96:97], v[72:73] op_sel_hi:[0,1,1]
	v_add_f32_e32 v0, 1.0, v0
	v_rcp_f32_e32 v98, v0
	v_mul_f32_e32 v0, 0xbfb8aa3b, v93
	v_exp_f32_e32 v0, v0
	v_readlane_b32 s14, v87, s15
	v_readlane_b32 s16, v88, s15
	s_add_i32 s5, s5, 4
	v_add_f32_e32 v0, 1.0, v0
	v_rcp_f32_e32 v99, v0
	s_cmp_lg_u32 s5, 16
	v_pk_mul_f32 v[92:93], v[92:93], v[98:99]
	s_nop 0
	v_pk_mul_f32 v[92:93], v[96:97], v[92:93]
	s_nop 0
	v_cvt_pk_bf16_f32 v0, v92, v93
	v_add_co_u32_e32 v92, vcc, s84, v74
	s_nop 1
	v_addc_co_u32_e32 v93, vcc, -1, v75, vcc
	global_store_dword v[92:93], v0, off offset:-1536
	v_add_u32_e32 v0, 48, v89
	s_waitcnt lgkmcnt(0)
	v_mov_b64_e32 v[96:97], v[110:111]
	v_mov_b64_e32 v[98:99], v[112:113]
	v_add_u32_e32 v89, 0x1040, v89
	s_waitcnt lgkmcnt(0)
	v_pk_fma_f32 v[92:93], v[66:67], s[14:15], v[96:97] op_sel_hi:[1,0,1] neg_lo:[1,0,0] neg_hi:[1,0,0]
	s_nop 0
	v_pk_fma_f32 v[92:93], s[16:17], v[92:93], v[70:71] op_sel_hi:[0,1,1]
	v_mul_f32_e32 v0, 0xbfb8aa3b, v92
	v_exp_f32_e32 v0, v0
	v_pk_fma_f32 v[96:97], v[68:69], s[14:15], v[98:99] op_sel_hi:[1,0,1] neg_lo:[1,0,0] neg_hi:[1,0,0]
	v_add_f32_e32 v0, 1.0, v0
	v_rcp_f32_e32 v98, v0
	v_mul_f32_e32 v0, 0xbfb8aa3b, v93
	v_exp_f32_e32 v0, v0
	v_pk_fma_f32 v[96:97], s[16:17], v[96:97], v[72:73] op_sel_hi:[0,1,1]
	v_add_f32_e32 v0, 1.0, v0
	v_rcp_f32_e32 v99, v0
	s_nop 0
	v_pk_mul_f32 v[92:93], v[92:93], v[98:99]
	s_nop 0
	v_pk_mul_f32 v[92:93], v[96:97], v[92:93]
	s_nop 0
	v_cvt_pk_bf16_f32 v0, v92, v93
	global_store_dword v[74:75], v0, off
	v_lshl_add_u64 v[74:75], v[74:75], 0, s[88:89]
	s_cbranch_scc1 .LBB0_1897
	s_barrier
	ds_write2_b32 v130, v2, v18 offset1:16
	ds_write2_b32 v114, v3, v19 offset0:4 offset1:20
	ds_write2_b32 v115, v4, v20 offset0:8 offset1:24
	ds_write2_b32 v116, v5, v21 offset0:12 offset1:28
	ds_write2_b32 v117, v6, v22 offset0:64 offset1:80
	ds_write2_b32 v82, v7, v23 offset0:68 offset1:84
	ds_write2_b32 v83, v8, v24 offset0:72 offset1:88
	ds_write2_b32 v84, v9, v25 offset0:76 offset1:92
	ds_write2_b32 v85, v10, v26 offset0:128 offset1:144
	ds_write2_b32 v78, v11, v27 offset0:132 offset1:148
	ds_write2_b32 v79, v12, v28 offset0:136 offset1:152
	ds_write2_b32 v76, v13, v29 offset0:140 offset1:156
	ds_write2_b32 v94, v14, v30 offset0:192 offset1:208
	ds_write2_b32 v77, v15, v31 offset0:196 offset1:212
	ds_write2_b32 v80, v16, v32 offset0:200 offset1:216
	ds_write2_b32 v81, v17, v33 offset0:204 offset1:220
	ds_write2_b32 v130, v34, v50 offset0:128 offset1:144
	ds_write2_b32 v114, v35, v51 offset0:132 offset1:148
	ds_write2_b32 v115, v36, v52 offset0:136 offset1:152
	ds_write2_b32 v116, v37, v53 offset0:140 offset1:156
	ds_write2_b32 v117, v38, v54 offset0:192 offset1:208
	ds_write2_b32 v82, v39, v55 offset0:196 offset1:212
	ds_write2_b32 v83, v40, v56 offset0:200 offset1:216
	ds_write2_b32 v84, v41, v57 offset0:204 offset1:220
	ds_write2_b32 v78, v42, v58 offset1:16
	ds_write2_b32 v79, v43, v59 offset0:4 offset1:20
	ds_write2_b32 v76, v44, v60 offset0:8 offset1:24
	ds_write2_b32 v90, v45, v61 offset0:12 offset1:28
	ds_write2_b32 v77, v46, v62 offset0:64 offset1:80
	ds_write2_b32 v80, v47, v63 offset0:68 offset1:84
	ds_write2_b32 v81, v48, v64 offset0:72 offset1:88
	ds_write2_b32 v86, v49, v65 offset0:76 offset1:92
	s_mov_b64 s[14:15], s[70:71]
	v_mov_b32_e32 v22, v178
	s_waitcnt lgkmcnt(0)
	s_barrier
; DI float fxc(const i64* p) { return (float)(*p) * FXC_INV; }
; DI RowStat row_stat(const i64* st, int row) {
;   float s = (float)st[2 * (size_t)row] * FXS_INV, q = (float)st[2 * (size_t)row + 1] * FXS_INV;
;   float mu = s * (1.f / 1024.f);
;   float var = fmaxf(q * (1.f / 1024.f) - mu * mu, 0.f);
;   RowStat r; r.mu = mu; r.rstd = rsqrtf(var + 1e-5f); return r;
; }
; DI void epi_rows(const Params& p, int L, int ekind, const float* T, int rbase, int bcol) {
;     ...
;       float csg0 = 0, csg1 = 0, csu0 = 0, csu1 = 0, bwg0 = 0, bwg1 = 0, bwu0 = 0, bwu1 = 0;
;       float mu_l = 0.f, rstd_l = 1.f;
;       if (st) { const i64* q = cs + co + bcol + c; const i64* r = bw + co + bcol + c;
;         csg0 = fxc(q); csg1 = fxc(q + 1); csu0 = fxc(q + 128); csu1 = fxc(q + 129); bwg0 = fxc(r); bwg1 = fxc(r + 1); bwu0 = fxc(r + 128); bwu1 = fxc(r + 129);
;         RowStat rs = row_stat(st, myrow); mu_l = rs.mu; rstd_l = rs.rstd; }
	s_add_u32 s16, s14, s10
	v_readfirstlane_b32 s5, v22
	s_addc_u32 s17, s15, s11
	s_ashr_i32 s10, s5, 2
	s_and_b32 s11, s10, -16
	s_add_i32 s11, s11, s4
	s_add_u32 s4, s14, s12
	s_addc_u32 s5, s15, s13
	v_lshlrev_b32_e32 v0, 4, v22
	s_add_u32 s8, s16, s8
	v_and_b32_e32 v0, 0x3f0, v0
	s_addc_u32 s9, s17, s9
	v_lshl_add_u64 v[14:15], s[8:9], 0, v[0:1]
	s_mov_b32 s8, 0x3a0000
	v_add_co_u32_e32 v2, vcc, s8, v14
	s_mov_b64 s[8:9], 0x3a0800
	s_nop 0
	v_addc_co_u32_e32 v3, vcc, 0, v15, vcc
	flat_load_dwordx4 v[2:5], v[2:3] offset:2048
	v_lshl_add_u64 v[6:7], v[14:15], 0, s[8:9]
	flat_load_dwordx4 v[6:9], v[6:7] offset:1024
	s_mov_b32 s8, 0x3db000
	v_add_co_u32_e32 v10, vcc, s8, v14
	s_mov_b64 s[12:13], 0x3db800
	s_nop 0
	v_addc_co_u32_e32 v11, vcc, 0, v15, vcc
	flat_load_dwordx4 v[10:13], v[10:11] offset:2048
	v_lshl_add_u64 v[14:15], v[14:15], 0, s[12:13]
	flat_load_dwordx4 v[14:17], v[14:15] offset:1024
	v_and_or_b32 v18, v22, 15, s11
	v_ashrrev_i32_e32 v19, 31, v18
	v_lshl_add_u64 v[18:19], v[18:19], 4, s[4:5]
	s_mov_b32 s4, 0x82000
	v_add_co_u32_e32 v18, vcc, s4, v18
	s_mov_b32 s4, 0x3a800000
	s_nop 0
	v_addc_co_u32_e32 v19, vcc, 0, v19, vcc
	flat_load_dwordx4 v[18:21], v[18:19]
	s_lshr_b32 s5, s10, 4
	s_mulk_i32 s5, 0x4100
	s_add_i32 s5, s5, 0
	s_mov_b32 s12, 0x2f800000
	s_mov_b32 s8, 0
	s_waitcnt vmcnt(0) lgkmcnt(0)
	v_xor_b32_e32 v0, v4, v5
	v_ffbh_i32_e32 v23, v5
	v_ashrrev_i32_e32 v0, 31, v0
	v_add_u32_e32 v23, -1, v23
	v_add_u32_e32 v0, 32, v0
	v_min_u32_e32 v0, v23, v0
	v_lshlrev_b64 v[4:5], v0, v[4:5]
	v_xor_b32_e32 v24, v2, v3
	v_min_u32_e32 v4, 1, v4
	v_ffbh_i32_e32 v25, v3
	v_ashrrev_i32_e32 v24, 31, v24
	v_or_b32_e32 v4, v5, v4
	v_add_u32_e32 v25, -1, v25
	v_add_u32_e32 v24, 32, v24
	v_cvt_f32_i32_e32 v4, v4
	v_min_u32_e32 v23, v25, v24
	v_lshlrev_b64 v[2:3], v23, v[2:3]
	v_xor_b32_e32 v26, v8, v9
	v_sub_u32_e32 v0, 32, v0
	v_min_u32_e32 v2, 1, v2
	v_ashrrev_i32_e32 v26, 31, v26
	v_or_b32_e32 v2, v3, v2
	v_ldexp_f32 v3, v4, v0
	v_ffbh_i32_e32 v0, v9
	v_add_u32_e32 v26, 32, v26
	v_add_u32_e32 v0, -1, v0
	v_min_u32_e32 v0, v0, v26
	v_lshlrev_b64 v[4:5], v0, v[8:9]
	v_min_u32_e32 v4, 1, v4
	v_or_b32_e32 v4, v5, v4
	v_cvt_f32_i32_e32 v4, v4
	v_sub_u32_e32 v0, 32, v0
	v_cvt_f32_i32_e32 v2, v2
	v_sub_u32_e32 v23, 32, v23
	v_ldexp_f32 v5, v4, v0
	v_xor_b32_e32 v0, v6, v7
	v_ashrrev_i32_e32 v0, 31, v0
	v_ffbh_i32_e32 v4, v7
	v_add_u32_e32 v0, 32, v0
	v_add_u32_e32 v4, -1, v4
	v_min_u32_e32 v0, v4, v0
	v_lshlrev_b64 v[6:7], v0, v[6:7]
	v_min_u32_e32 v4, 1, v6
	v_xor_b32_e32 v6, v12, v13
	v_or_b32_e32 v4, v7, v4
	v_ashrrev_i32_e32 v6, 31, v6
	v_ffbh_i32_e32 v7, v13
	v_add_u32_e32 v6, 32, v6
	v_add_u32_e32 v7, -1, v7
	v_min_u32_e32 v8, v7, v6
	v_lshlrev_b64 v[6:7], v8, v[12:13]
	v_min_u32_e32 v6, 1, v6
	v_cvt_f32_i32_e32 v4, v4
	v_or_b32_e32 v6, v7, v6
	v_cvt_f32_i32_e32 v6, v6
	v_sub_u32_e32 v0, 32, v0
	v_ldexp_f32 v4, v4, v0
	v_sub_u32_e32 v0, 32, v8
	v_ldexp_f32 v7, v6, v0
	v_xor_b32_e32 v0, v10, v11
	v_ashrrev_i32_e32 v0, 31, v0
	v_ffbh_i32_e32 v6, v11
	v_add_u32_e32 v0, 32, v0
	v_add_u32_e32 v6, -1, v6
	v_min_u32_e32 v0, v6, v0
	v_lshlrev_b64 v[8:9], v0, v[10:11]
	v_min_u32_e32 v6, 1, v8
	v_xor_b32_e32 v8, v16, v17
	v_or_b32_e32 v6, v9, v6
	v_ashrrev_i32_e32 v8, 31, v8
	v_ffbh_i32_e32 v9, v17
	v_add_u32_e32 v8, 32, v8
	v_add_u32_e32 v9, -1, v9
	v_min_u32_e32 v10, v9, v8
	v_lshlrev_b64 v[8:9], v10, v[16:17]
	v_min_u32_e32 v8, 1, v8
	v_cvt_f32_i32_e32 v6, v6
	v_or_b32_e32 v8, v9, v8
	v_cvt_f32_i32_e32 v8, v8
	v_sub_u32_e32 v0, 32, v0
	v_ldexp_f32 v6, v6, v0
	v_sub_u32_e32 v0, 32, v10
	v_ldexp_f32 v9, v8, v0
	v_xor_b32_e32 v0, v14, v15
	v_ashrrev_i32_e32 v0, 31, v0
	v_ffbh_i32_e32 v8, v15
	v_add_u32_e32 v0, 32, v0
	v_add_u32_e32 v8, -1, v8
	v_min_u32_e32 v0, v8, v0
	v_lshlrev_b64 v[10:11], v0, v[14:15]
	v_min_u32_e32 v8, 1, v10
	v_xor_b32_e32 v10, v18, v19
	v_or_b32_e32 v8, v11, v8
	v_ashrrev_i32_e32 v10, 31, v10
	v_ffbh_i32_e32 v11, v19
	v_add_u32_e32 v10, 32, v10
	v_add_u32_e32 v11, -1, v11
	v_min_u32_e32 v12, v11, v10
	v_lshlrev_b64 v[10:11], v12, v[18:19]
	v_min_u32_e32 v10, 1, v10
	v_or_b32_e32 v10, v11, v10
	v_cvt_f32_i32_e32 v13, v10
	v_xor_b32_e32 v10, v20, v21
	v_ashrrev_i32_e32 v10, 31, v10
	v_ffbh_i32_e32 v11, v21
	v_add_u32_e32 v10, 32, v10
	v_add_u32_e32 v11, -1, v11
	v_min_u32_e32 v14, v11, v10
	v_lshlrev_b64 v[10:11], v14, v[20:21]
	v_min_u32_e32 v10, 1, v10
	v_or_b32_e32 v10, v11, v10
	v_cvt_f32_i32_e32 v10, v10
	v_sub_u32_e32 v12, 32, v12
	v_ldexp_f32 v11, v13, v12
	v_mul_f32_e32 v11, 0x33800000, v11
	v_sub_u32_e32 v12, 32, v14
	v_ldexp_f32 v10, v10, v12
	v_mul_f32_e32 v12, 0x3a800000, v11
	v_mul_f32_e32 v10, 0x33800000, v10
	v_mul_f32_e32 v11, v12, v12
	v_fma_f32 v10, v10, s4, -v11
	v_max_f32_e32 v10, 0, v10
	v_add_f32_e32 v10, 0x3727c5ac, v10
	s_mov_b32 s4, 0x800000
	v_mul_f32_e32 v11, 0x4b800000, v10
	v_cmp_gt_f32_e32 vcc, s4, v10
	v_cvt_f32_i32_e32 v8, v8
	v_sub_u32_e32 v0, 32, v0
	v_cndmask_b32_e32 v10, v10, v11, vcc
	v_rsq_f32_e32 v10, v10
	v_ldexp_f32 v8, v8, v0
	s_mul_hi_i32 s4, s11, 0x1600
	s_mulk_i32 s11, 0x1600
	v_mul_f32_e32 v0, 0x45800000, v10
	v_cndmask_b32_e32 v13, v10, v0, vcc
	v_and_b32_e32 v0, 63, v22
	v_lshl_add_u32 v14, v0, 3, s5
	s_add_u32 s5, s14, s11
	s_addc_u32 s4, s15, s4
	s_add_u32 s5, s5, s6
	s_addc_u32 s6, s4, s7
	s_add_u32 s4, s5, 0xa0d1c00
	v_ldexp_f32 v2, v2, v23
	v_lshlrev_b32_e32 v0, 2, v0
	s_addc_u32 s5, s6, 0
	v_pk_mul_f32 v[2:3], v[2:3], s[12:13] op_sel_hi:[1,0]
	v_pk_mul_f32 v[4:5], v[4:5], s[12:13] op_sel_hi:[1,0]
	v_pk_mul_f32 v[6:7], v[6:7], s[12:13] op_sel_hi:[1,0]
	v_pk_mul_f32 v[8:9], v[8:9], s[12:13] op_sel_hi:[1,0]
	v_lshl_add_u64 v[10:11], s[4:5], 0, v[0:1]
; DI unsigned pack2(float a, float b) { fl2_t v = {a, b}; bf2_t r = __builtin_convertvector(v, bf2_t); return __builtin_bit_cast(unsigned, r); }
; DI float sigmoidf_(float x) { return __builtin_amdgcn_rcpf(1.f + __builtin_amdgcn_exp2f(-1.4426950408889634f * x)); }
; DI float rl(float v, int srclane) { return __int_as_float(__builtin_amdgcn_readlane(__float_as_int(v), srclane)); }
; DI void epi_rows(const Params& p, int L, int ekind, const float* T, int rbase, int bcol) {
;     ...
;       for (int i = 0; i < 16; ++i) {
;         const float mu = rl(mu_l, i), rstd = rl(rstd_l, i);
;         const float* tr = T + (lr0 + i) * TSTR + c;
;         float g0 = rstd * (tr[0] - mu * csg0) + bwg0, g1 = rstd * (tr[1] - mu * csg1) + bwg1;
;         float u0 = rstd * (tr[128] - mu * csu0) + bwu0, u1 = rstd * (tr[129] - mu * csu1) + bwu1;
;         float a0 = g0 * sigmoidf_(g0) * u0, a1 = g1 * sigmoidf_(g1) * u1;
;         stg<unsigned>(ap + (size_t)i * DFF, pack2(a0, a1));
;       }
.LBB0_1899:
	ds_read2st64_b64 v[16:19], v14 offset1:1
	ds_read2_b64 v[102:105], v14 offset0:130 offset1:194
	v_add_u32_e32 v118, 32, v14
	ds_read2st64_b64 v[106:109], v118 offset0:4 offset1:5
	v_add_u32_e32 v118, 48, v14
	ds_read2st64_b64 v[110:113], v118 offset0:6 offset1:7
	v_readlane_b32 s4, v12, s8
	v_readlane_b32 s6, v13, s8
	s_waitcnt lgkmcnt(3)
	v_pk_fma_f32 v[16:17], v[2:3], s[4:5], v[16:17] op_sel_hi:[1,0,1] neg_lo:[1,0,0] neg_hi:[1,0,0]
	s_nop 0
	v_pk_fma_f32 v[16:17], s[6:7], v[16:17], v[6:7] op_sel_hi:[0,1,1]
	v_mul_f32_e32 v0, 0xbfb8aa3b, v16
	v_exp_f32_e32 v0, v0
	v_pk_fma_f32 v[18:19], v[4:5], s[4:5], v[18:19] op_sel_hi:[1,0,1] neg_lo:[1,0,0] neg_hi:[1,0,0]
	s_add_i32 s5, s8, 1
	v_pk_fma_f32 v[18:19], s[6:7], v[18:19], v[8:9] op_sel_hi:[0,1,1]
	v_add_f32_e32 v0, 1.0, v0
	v_rcp_f32_e32 v20, v0
	v_mul_f32_e32 v0, 0xbfb8aa3b, v17
	v_exp_f32_e32 v0, v0
	v_readlane_b32 s4, v12, s5
	v_readlane_b32 s6, v13, s5
	v_add_f32_e32 v0, 1.0, v0
	v_rcp_f32_e32 v21, v0
	s_nop 0
	v_pk_mul_f32 v[16:17], v[16:17], v[20:21]
	s_nop 0
	v_pk_mul_f32 v[16:17], v[18:19], v[16:17]
	s_nop 0
	v_cvt_pk_bf16_f32 v0, v16, v17
	v_add_co_u32_e32 v16, vcc, s22, v10
	s_nop 1
	v_addc_co_u32_e32 v17, vcc, -1, v11, vcc
	global_store_dword v[16:17], v0, off offset:-512
	s_waitcnt lgkmcnt(2)
	v_mov_b64_e32 v[16:17], v[102:103]
	v_mov_b64_e32 v[18:19], v[104:105]
	s_waitcnt lgkmcnt(2)
	v_pk_fma_f32 v[16:17], v[2:3], s[4:5], v[16:17] op_sel_hi:[1,0,1] neg_lo:[1,0,0] neg_hi:[1,0,0]
	s_nop 0
	v_pk_fma_f32 v[16:17], s[6:7], v[16:17], v[6:7] op_sel_hi:[0,1,1]
	v_mul_f32_e32 v0, 0xbfb8aa3b, v16
	v_exp_f32_e32 v0, v0
	v_pk_fma_f32 v[18:19], v[4:5], s[4:5], v[18:19] op_sel_hi:[1,0,1] neg_lo:[1,0,0] neg_hi:[1,0,0]
	s_add_i32 s5, s8, 2
	v_pk_fma_f32 v[18:19], s[6:7], v[18:19], v[8:9] op_sel_hi:[0,1,1]
	v_add_f32_e32 v0, 1.0, v0
	v_rcp_f32_e32 v20, v0
	v_mul_f32_e32 v0, 0xbfb8aa3b, v17
	v_exp_f32_e32 v0, v0
	v_readlane_b32 s4, v12, s5
	v_readlane_b32 s6, v13, s5
	v_add_f32_e32 v0, 1.0, v0
	v_rcp_f32_e32 v21, v0
	s_nop 0
	v_pk_mul_f32 v[16:17], v[16:17], v[20:21]
	s_nop 0
	v_pk_mul_f32 v[16:17], v[18:19], v[16:17]
	s_nop 0
	v_cvt_pk_bf16_f32 v0, v16, v17
	v_add_co_u32_e32 v16, vcc, s83, v10
	s_nop 1
	v_addc_co_u32_e32 v17, vcc, -1, v11, vcc
	global_store_dword v[16:17], v0, off offset:-3072
	v_add_u32_e32 v0, 32, v14
	s_waitcnt lgkmcnt(1)
	v_mov_b64_e32 v[16:17], v[106:107]
	v_mov_b64_e32 v[18:19], v[108:109]
	s_waitcnt lgkmcnt(1)
	v_pk_fma_f32 v[16:17], v[2:3], s[4:5], v[16:17] op_sel_hi:[1,0,1] neg_lo:[1,0,0] neg_hi:[1,0,0]
	s_nop 0
	v_pk_fma_f32 v[16:17], s[6:7], v[16:17], v[6:7] op_sel_hi:[0,1,1]
	v_mul_f32_e32 v0, 0xbfb8aa3b, v16
	v_exp_f32_e32 v0, v0
	v_pk_fma_f32 v[18:19], v[4:5], s[4:5], v[18:19] op_sel_hi:[1,0,1] neg_lo:[1,0,0] neg_hi:[1,0,0]
	s_add_i32 s5, s8, 3
	v_pk_fma_f32 v[18:19], s[6:7], v[18:19], v[8:9] op_sel_hi:[0,1,1]
	v_add_f32_e32 v0, 1.0, v0
	v_rcp_f32_e32 v20, v0
	v_mul_f32_e32 v0, 0xbfb8aa3b, v17
	v_exp_f32_e32 v0, v0
	v_readlane_b32 s4, v12, s5
	v_readlane_b32 s6, v13, s5
	s_add_i32 s8, s8, 4
	v_add_f32_e32 v0, 1.0, v0
	v_rcp_f32_e32 v21, v0
	s_cmp_lg_u32 s8, 16
	v_pk_mul_f32 v[16:17], v[16:17], v[20:21]
	s_nop 0
	v_pk_mul_f32 v[16:17], v[18:19], v[16:17]
	s_nop 0
	v_cvt_pk_bf16_f32 v0, v16, v17
	v_add_co_u32_e32 v16, vcc, s84, v10
	s_nop 1
	v_addc_co_u32_e32 v17, vcc, -1, v11, vcc
	global_store_dword v[16:17], v0, off offset:-1536
	v_add_u32_e32 v0, 48, v14
	s_waitcnt lgkmcnt(0)
	v_mov_b64_e32 v[16:17], v[110:111]
	v_mov_b64_e32 v[18:19], v[112:113]
	v_add_u32_e32 v14, 0x1040, v14
	s_waitcnt lgkmcnt(0)
	v_pk_fma_f32 v[16:17], v[2:3], s[4:5], v[16:17] op_sel_hi:[1,0,1] neg_lo:[1,0,0] neg_hi:[1,0,0]
	s_nop 0
	v_pk_fma_f32 v[16:17], s[6:7], v[16:17], v[6:7] op_sel_hi:[0,1,1]
	v_mul_f32_e32 v0, 0xbfb8aa3b, v16
	v_exp_f32_e32 v0, v0
	v_pk_fma_f32 v[18:19], v[4:5], s[4:5], v[18:19] op_sel_hi:[1,0,1] neg_lo:[1,0,0] neg_hi:[1,0,0]
	v_add_f32_e32 v0, 1.0, v0
	v_rcp_f32_e32 v20, v0
	v_mul_f32_e32 v0, 0xbfb8aa3b, v17
	v_exp_f32_e32 v0, v0
	v_pk_fma_f32 v[18:19], s[6:7], v[18:19], v[8:9] op_sel_hi:[0,1,1]
	v_add_f32_e32 v0, 1.0, v0
	v_rcp_f32_e32 v21, v0
	s_nop 0
	v_pk_mul_f32 v[16:17], v[16:17], v[20:21]
	s_nop 0
	v_pk_mul_f32 v[16:17], v[18:19], v[16:17]
	s_nop 0
	v_cvt_pk_bf16_f32 v0, v16, v17
	global_store_dword v[10:11], v0, off
	v_lshl_add_u64 v[10:11], v[10:11], 0, s[88:89]
	s_cbranch_scc1 .LBB0_1899
	s_barrier
	v_readlane_b32 s4, v254, 3
	s_add_i32 s28, s28, s4
	s_cmpk_lt_i32 s28, 0xb2c
	v_readlane_b32 s5, v254, 4
	s_cbranch_scc1 .LBB0_1886
